# F1 merge GEMM: L2 touch-ahead of HBM-resident A operand 3 K-tiles ahead of the LDS-DMA
# baseline (speedup 1.0000x reference)
.LBB0_162:
	s_lshl_b32 s0, s11, 11
	s_add_u32 s2, s94, s0
	s_addc_u32 s3, s95, 0
	v_lshl_add_u64 v[0:1], s[2:3], 0, v[94:95]
	v_lshl_add_u64 v[0:1], v[0:1], 0, v[66:67]
	global_load_dwordx2 v[176:177], v[0:1], off
	global_load_dwordx2 v[174:175], v[0:1], off offset:32
	global_load_dwordx2 v[172:173], v[0:1], off offset:64
	global_load_dwordx2 v[170:171], v[0:1], off offset:96
	v_lshl_add_u64 v[0:1], s[2:3], 0, v[114:115]
	v_lshl_add_u64 v[0:1], v[0:1], 0, v[66:67]
	global_load_dwordx2 v[168:169], v[0:1], off
	global_load_dwordx2 v[166:167], v[0:1], off offset:32
	global_load_dwordx2 v[164:165], v[0:1], off offset:64
	global_load_dwordx2 v[162:163], v[0:1], off offset:96
	v_lshl_add_u64 v[0:1], s[2:3], 0, v[126:127]
	v_lshl_add_u64 v[0:1], v[0:1], 0, v[66:67]
	global_load_dwordx2 v[160:161], v[0:1], off
	global_load_dwordx2 v[158:159], v[0:1], off offset:32
	global_load_dwordx2 v[156:157], v[0:1], off offset:64
	global_load_dwordx2 v[154:155], v[0:1], off offset:96
	v_lshl_add_u64 v[0:1], s[2:3], 0, v[128:129]
	v_lshl_add_u64 v[0:1], v[0:1], 0, v[66:67]
	global_load_dwordx2 v[152:153], v[0:1], off
	global_load_dwordx2 v[150:151], v[0:1], off offset:32
	global_load_dwordx2 v[148:149], v[0:1], off offset:64
	global_load_dwordx2 v[146:147], v[0:1], off offset:96
	s_cmp_eq_u32 s11, 1
	s_mov_b32 s3, 0x530000
	s_cselect_b32 s0, s88, s82
	s_cselect_b32 s2, s89, s83
	s_cselect_b32 s4, s3, 0x630000
	s_cselect_b32 s12, 16, 8
	s_cselect_b32 s13, 10, 9
	s_cmp_eq_u32 s11, 0
	s_cselect_b32 s3, s81, s2
	s_cselect_b32 s2, s80, s0
	s_cselect_b32 s0, 0x4b0000, s4
	s_lshl_b32 s0, s0, 1
	v_mov_b32_e32 v4, v204
	s_add_u32 s4, s97, s0
	v_readfirstlane_b32 s14, v4
	s_addc_u32 s5, s79, 0
	s_ashr_i32 s15, s14, 6
	v_bfe_u32 v0, v4, 3, 3
	s_and_b32 s16, s15, 1
	v_lshl_or_b32 v5, s15, 3, v0
	v_and_b32_e32 v0, 7, v4
	s_lshl_b32 s0, s16, 2
	v_bfe_u32 v6, v4, 4, 2
	v_bitop3_b32 v7, s0, v0, v6 bitop3:0x36
	v_add_u32_e32 v0, s9, v5
	v_and_b32_e32 v250, 0xff, v204
	v_add_u32_e32 v250, s9, v250
	s_add_i32 vcc_lo, s13, 1
	v_lshlrev_b32_e32 v250, vcc_lo, v250
	v_ashrrev_i32_e32 v1, 31, v0
	v_lshlrev_b64 v[2:3], s13, v[0:1]
	v_lshl_add_u64 v[2:3], v[2:3], 1, s[2:3]
	v_lshlrev_b32_e32 v188, 4, v7
	v_lshl_add_u64 v[178:179], v[2:3], 0, v[188:189]
	v_add_u32_e32 v2, 64, v0
	v_ashrrev_i32_e32 v3, 31, v2
	v_lshlrev_b64 v[2:3], s13, v[2:3]
	v_lshl_add_u64 v[2:3], v[2:3], 1, s[2:3]
	v_lshl_add_u64 v[180:181], v[2:3], 0, v[188:189]
	v_add_u32_e32 v2, 0x80, v0
	v_add_u32_e32 v0, 0xc0, v0
	v_ashrrev_i32_e32 v1, 31, v0
	v_lshlrev_b64 v[0:1], s13, v[0:1]
	v_ashrrev_i32_e32 v3, 31, v2
	v_lshl_add_u64 v[0:1], v[0:1], 1, s[2:3]
	v_lshlrev_b64 v[2:3], s13, v[2:3]
	v_lshl_add_u64 v[184:185], v[0:1], 0, v[188:189]
	v_add_u32_e32 v0, s10, v5
	v_lshl_add_u64 v[2:3], v[2:3], 1, s[2:3]
	v_ashrrev_i32_e32 v1, 31, v0
	v_lshl_add_u64 v[182:183], v[2:3], 0, v[188:189]
	v_lshlrev_b64 v[2:3], s13, v[0:1]
	v_add_u32_e32 v0, 64, v0
	v_ashrrev_i32_e32 v1, 31, v0
	s_lshl_b32 s2, s15, 10
	v_lshlrev_b64 v[0:1], s13, v[0:1]
	s_add_i32 s13, s2, 0
	s_mov_b32 m0, s13
	v_lshl_add_u64 v[2:3], v[2:3], 1, s[4:5]
	global_load_lds_dwordx4 v[178:179], off
	s_add_i32 m0, s13, 0x2000
	v_lshl_add_u64 v[186:187], v[2:3], 0, v[188:189]
	global_load_lds_dwordx4 v[180:181], off
	s_add_i32 m0, s13, 0x4000
	v_lshl_add_u64 v[0:1], v[0:1], 1, s[4:5]
	global_load_lds_dwordx4 v[182:183], off
	s_add_i32 m0, s13, 0x6000
	v_lshl_add_u64 v[190:191], v[0:1], 0, v[188:189]
	global_load_lds_dwordx4 v[184:185], off
	s_add_i32 m0, s13, 0x8000
	v_lshl_add_u64 v[0:1], v[178:179], 0, s[92:93]
	global_load_lds_dwordx4 v[186:187], off
	s_add_i32 m0, s13, 0xa000
	s_lshr_b32 s2, s14, 1
	global_load_lds_dwordx4 v[190:191], off
	s_add_i32 m0, s13, 0xc000
	s_and_b32 s2, s2, 0x1ffffc0
	global_load_lds_dwordx4 v[0:1], off
	v_lshl_add_u64 v[0:1], v[180:181], 0, s[92:93]
	s_add_i32 m0, s13, 0xe000
	s_movk_i32 s0, 0x80
	global_load_lds_dwordx4 v[0:1], off
	v_lshl_add_u64 v[0:1], v[182:183], 0, s[92:93]
	s_add_i32 m0, s13, 0x10000
	s_lshl_b32 s14, s16, 13
	global_load_lds_dwordx4 v[0:1], off
	v_lshl_add_u64 v[0:1], v[184:185], 0, s[92:93]
	s_add_i32 m0, s13, 0x12000
	s_mov_b32 s15, 0
	global_load_lds_dwordx4 v[0:1], off
	v_lshl_add_u64 v[0:1], v[186:187], 0, s[92:93]
	s_add_i32 m0, s13, 0x14000
	s_mov_b32 s16, 0
	global_load_lds_dwordx4 v[0:1], off
	v_lshl_add_u64 v[0:1], v[190:191], 0, s[92:93]
	s_add_i32 m0, s13, 0x16000
	v_mov_b32_e32 v2, v192
	global_load_lds_dwordx4 v[0:1], off
	s_cmp_eq_u32 s11, 1
	s_cselect_b32 vcc_lo, s88, s82
	s_cselect_b32 vcc_hi, s89, s83
	s_cmp_eq_u32 s11, 0
	s_cselect_b32 vcc_lo, s80, vcc_lo
	s_cselect_b32 vcc_hi, s81, vcc_hi
	global_load_dword v251, v250, vcc offset:256
	global_load_dword v251, v250, vcc offset:384
	global_load_dword v251, v250, vcc offset:512
	s_waitcnt vmcnt(9)
	v_bfe_u32 v1, v4, 1, 3
	s_waitcnt lgkmcnt(0)
	s_barrier
	v_and_b32_e32 v0, 15, v4
	v_xor_b32_e32 v1, v6, v1
	v_lshlrev_b32_e32 v188, 4, v1
	v_or_b32_e32 v1, s2, v0
	v_lshlrev_b32_e32 v193, 7, v1
	v_lshlrev_b32_e32 v194, 7, v0
	v_xor_b32_e32 v195, 64, v188
	v_mov_b32_e32 v0, 0
	v_mov_b32_e32 v1, v192
	v_mov_b32_e32 v3, v192
	v_mov_b32_e32 v4, 0
	v_mov_b32_e32 v5, v192
	v_mov_b32_e32 v6, v192
	v_mov_b32_e32 v7, v192
	v_mov_b32_e32 v8, 0
	v_mov_b32_e32 v9, v192
	v_mov_b32_e32 v10, v192
	v_mov_b32_e32 v11, v192
	v_mov_b32_e32 v12, 0
	v_mov_b32_e32 v13, v192
	v_mov_b32_e32 v14, v192
	v_mov_b32_e32 v15, v192
	v_mov_b32_e32 v16, 0
	v_mov_b32_e32 v17, v192
	v_mov_b32_e32 v18, v192
	v_mov_b32_e32 v19, v192
	v_mov_b32_e32 v20, 0
	v_mov_b32_e32 v21, v192
	v_mov_b32_e32 v22, v192
	v_mov_b32_e32 v23, v192
	v_mov_b32_e32 v24, 0
	v_mov_b32_e32 v25, v192
	v_mov_b32_e32 v26, v192
	v_mov_b32_e32 v27, v192
	v_mov_b32_e32 v28, 0
	v_mov_b32_e32 v29, v192
	v_mov_b32_e32 v30, v192
	v_mov_b32_e32 v31, v192
	v_mov_b32_e32 v32, 0
	v_mov_b32_e32 v33, v192
	v_mov_b32_e32 v34, v192
	v_mov_b32_e32 v35, v192
	v_mov_b32_e32 v36, 0
	v_mov_b32_e32 v37, v192
	v_mov_b32_e32 v38, v192
	v_mov_b32_e32 v39, v192
	v_mov_b32_e32 v40, 0
	v_mov_b32_e32 v41, v192
	v_mov_b32_e32 v42, v192
	v_mov_b32_e32 v43, v192
	v_mov_b32_e32 v44, 0
	v_mov_b32_e32 v45, v192
	v_mov_b32_e32 v46, v192
	v_mov_b32_e32 v47, v192
	v_mov_b32_e32 v48, 0
	v_mov_b32_e32 v49, v192
	v_mov_b32_e32 v50, v192
	v_mov_b32_e32 v51, v192
	v_mov_b32_e32 v52, 0
	v_mov_b32_e32 v53, v192
	v_mov_b32_e32 v54, v192
	v_mov_b32_e32 v55, v192
	v_mov_b32_e32 v56, 0
	v_mov_b32_e32 v57, v192
	v_mov_b32_e32 v58, v192
	v_mov_b32_e32 v59, v192
	v_mov_b32_e32 v60, 0
	v_mov_b32_e32 v61, v192
	v_mov_b32_e32 v62, v192
	v_mov_b32_e32 v63, v192
	s_branch .LBB0_164

.LBB0_166:
	s_andn2_b64 vcc, exec, s[4:5]
	s_cbranch_vccnz .LBB0_168
	s_add_i32 s4, s18, 0xffff4000
	s_cmp_lg_u32 s15, 0
	s_cselect_b32 s17, s4, 0x18000
	s_lshl_b64 s[4:5], s[0:1], 1
	s_add_i32 s17, s13, s17
	v_lshl_add_u64 v[196:197], v[178:179], 0, s[4:5]
	s_mov_b32 m0, s17
	s_nop 0
	global_load_lds_dwordx4 v[196:197], off
	v_lshl_add_u64 v[196:197], v[180:181], 0, s[4:5]
	s_add_i32 m0, s17, 0x2000
	s_nop 0
	global_load_lds_dwordx4 v[196:197], off
	v_lshl_add_u64 v[196:197], v[182:183], 0, s[4:5]
	s_add_i32 m0, s17, 0x4000
	s_nop 0
	global_load_lds_dwordx4 v[196:197], off
	v_lshl_add_u64 v[196:197], v[184:185], 0, s[4:5]
	s_add_i32 m0, s17, 0x6000
	s_nop 0
	global_load_lds_dwordx4 v[196:197], off
	v_lshl_add_u64 v[196:197], v[186:187], 0, s[4:5]
	s_add_i32 m0, s17, 0x8000
	s_nop 0
	global_load_lds_dwordx4 v[196:197], off
	v_lshl_add_u64 v[196:197], v[190:191], 0, s[4:5]
	s_add_i32 m0, s17, 0xa000
	s_mov_b32 s17, s18
	global_load_lds_dwordx4 v[196:197], off
	s_cmp_eq_u32 s11, 1
	s_cselect_b32 vcc_lo, s88, s82
	s_cselect_b32 vcc_hi, s89, s83
	s_cmp_eq_u32 s11, 0
	s_cselect_b32 vcc_lo, s80, vcc_lo
	s_cselect_b32 vcc_hi, s81, vcc_hi
	s_add_u32 vcc_lo, vcc_lo, s4
	s_addc_u32 vcc_hi, vcc_hi, s5
	global_load_dword v251, v250, vcc offset:384

.LBB0_170:
	s_andn2_b64 vcc, exec, s[4:5]
	s_cbranch_vccnz .LBB0_163
	s_waitcnt vmcnt(8)
	s_waitcnt lgkmcnt(0)
	s_barrier
	s_branch .LBB0_163
